# attention partner-wave skew after the pair barrier lowered from 128 to 64 cycles (s_sleep 1)
# speedup vs baseline: 1.0092x; 1.0033x over previous
.Latt_even_entry:
	s_waitcnt vmcnt(0) lgkmcnt(0)
	s_barrier
	s_bitcmp1_b32 s97, 8
	s_cbranch_scc0 .Latt_no_skew
	s_sleep 1
